# NORM loop: 16 loads per row issued up front as global loads with counted vmcnt (was 6 serialized flat-load round trips per row)
# speedup vs baseline: 1.0092x; 1.0092x over previous
.LBB0_831:
	global_load_dwordx4 v[12:15], v[22:23], off
	global_load_dwordx4 v[8:11], v[22:23], off offset:1024
	global_load_dwordx4 v[4:7], v[22:23], off offset:2048
	global_load_dwordx4 v[0:3], v[22:23], off offset:3072
	s_ashr_i32 s5, s4, 13
	s_add_i32 s5, s11, s5
	s_ashr_i32 s14, s4, 11
	s_and_b64 s[8:9], s[0:1], exec
	s_cselect_b32 s5, s14, s5
	s_mul_i32 s8, s5, 0xc00
	s_ashr_i32 s9, s8, 31
	s_lshl_b64 s[8:9], s[8:9], 2
	s_add_u32 s14, s3, s8
	s_addc_u32 s15, s10, s9
	s_add_u32 s8, s14, 0x1000
	s_addc_u32 s9, s15, 0
	s_add_u32 s16, s20, s6
	s_addc_u32 s17, s21, s7
	v_lshl_add_u64 v[32:33], s[14:15], 0, v[204:205]
	v_lshl_add_u64 v[38:39], s[8:9], 0, v[204:205]
	v_lshl_add_u64 v[16:17], s[16:17], 0, v[204:205]
	global_load_dwordx4 v[100:103], v[32:33], off
	global_load_dwordx4 v[116:119], v[38:39], off
	global_load_dwordx4 v[132:135], v[16:17], off
	global_load_dwordx4 v[104:107], v[32:33], off offset:1024
	global_load_dwordx4 v[120:123], v[38:39], off offset:1024
	global_load_dwordx4 v[136:139], v[16:17], off offset:1024
	global_load_dwordx4 v[108:111], v[32:33], off offset:2048
	global_load_dwordx4 v[124:127], v[38:39], off offset:2048
	global_load_dwordx4 v[140:143], v[16:17], off offset:2048
	global_load_dwordx4 v[112:115], v[32:33], off offset:3072
	global_load_dwordx4 v[128:131], v[38:39], off offset:3072
	global_load_dwordx4 v[144:147], v[16:17], off offset:3072
	v_lshl_add_u64 v[22:23], v[22:23], 0, s[24:25]
	s_waitcnt vmcnt(12)
	v_pk_mul_f32 v[148:149], v[14:15], v[14:15]
	v_pk_mul_f32 v[150:151], v[12:13], v[12:13]
	s_nop 0
	v_pk_mov_b32 v[152:153], v[150:151], v[148:149] op_sel:[1,0]
	v_mov_b32_e32 v151, v149
	v_pk_add_f32 v[16:17], v[152:153], v[150:151]
	v_pk_mul_f32 v[148:149], v[10:11], v[10:11]
	v_pk_mul_f32 v[150:151], v[8:9], v[8:9]
	v_pk_add_f32 v[16:17], v[16:17], v[16:17] op_sel:[0,1] op_sel_hi:[1,0]
	v_pk_mov_b32 v[152:153], v[150:151], v[148:149] op_sel:[1,0]
	v_mov_b32_e32 v151, v149
	v_pk_add_f32 v[18:19], v[152:153], v[150:151]
	s_nop 0
	v_pk_add_f32 v[18:19], v[18:19], v[18:19] op_sel:[0,1] op_sel_hi:[1,0]
	v_mul_f32_e32 v30, v7, v7
	v_mul_f32_e32 v25, v0, v0
	v_mul_f32_e32 v27, v1, v1
	v_mov_b32_e32 v17, v25
	v_mov_b32_e32 v19, v27
	v_pk_add_f32 v[16:17], v[16:17], v[18:19]
	v_mul_f32_e32 v18, v5, v5
	v_mul_f32_e32 v29, v2, v2
	v_mul_f32_e32 v32, v3, v3
	v_pk_fma_f32 v[18:19], v[4:5], v[4:5], v[18:19] op_sel_hi:[1,1,0]
	v_pk_fma_f32 v[30:31], v[6:7], v[6:7], v[30:31] op_sel_hi:[1,1,0]
	v_mov_b32_e32 v19, v29
	v_mov_b32_e32 v31, v32
	v_pk_add_f32 v[18:19], v[18:19], v[30:31]
	s_nop 0
	v_pk_add_f32 v[16:17], v[16:17], v[18:19]
	s_nop 0
	v_add_f32_e32 v16, v16, v17
	ds_swizzle_b32 v17, v16 offset:swizzle(SWAP,1)
	v_mov_b32_e32 v25, v205
	v_mov_b32_e32 v27, v205
	v_mov_b32_e32 v29, v205
	s_waitcnt lgkmcnt(0)
	v_add_f32_e32 v16, v16, v17
	ds_swizzle_b32 v17, v16 offset:swizzle(SWAP,2)
	s_waitcnt lgkmcnt(0)
	v_add_f32_e32 v16, v16, v17
	ds_swizzle_b32 v17, v16 offset:swizzle(SWAP,4)
	s_waitcnt lgkmcnt(0)
	v_add_f32_e32 v16, v16, v17
	ds_swizzle_b32 v17, v16 offset:swizzle(SWAP,8)
	s_waitcnt lgkmcnt(0)
	v_add_f32_e32 v16, v16, v17
	ds_swizzle_b32 v17, v16 offset:swizzle(SWAP,16)
	s_waitcnt lgkmcnt(0)
	v_add_f32_e32 v16, v16, v17
	v_mov_b32_e32 v17, v220
	v_lshlrev_b32_e32 v17, 2, v17
	v_bitop3_b32 v17, v17, s88, v227 bitop3:0x6c
	ds_bpermute_b32 v17, v17, v16
	s_waitcnt lgkmcnt(0)
	v_add_f32_e32 v16, v16, v17
	v_fmamk_f32 v16, v16, 0x3a800000, v224
	v_cmp_gt_f32_e32 vcc, s19, v16
	v_mul_f32_e32 v17, 0x4b800000, v16
	s_nop 1
	v_cndmask_b32_e32 v16, v16, v17, vcc
	v_rsq_f32_e32 v16, v16
	s_nop 0
	v_mul_f32_e32 v17, 0x45800000, v16
	v_cndmask_b32_e32 v30, v16, v17, vcc
	s_nop 0
	v_pk_mul_f32 v[14:15], v[30:31], v[14:15] op_sel_hi:[0,1]
	v_pk_mul_f32 v[12:13], v[30:31], v[12:13] op_sel_hi:[0,1]
	v_pk_mul_f32 v[10:11], v[30:31], v[10:11] op_sel_hi:[0,1]
	v_pk_mul_f32 v[8:9], v[30:31], v[8:9] op_sel_hi:[0,1]
	v_pk_mul_f32 v[6:7], v[30:31], v[6:7] op_sel_hi:[0,1]
	v_pk_mul_f32 v[4:5], v[30:31], v[4:5] op_sel_hi:[0,1]
	v_pk_mul_f32 v[2:3], v[30:31], v[2:3] op_sel_hi:[0,1]
	v_pk_mul_f32 v[0:1], v[30:31], v[0:1] op_sel_hi:[0,1]
	s_waitcnt vmcnt(9)
	v_pk_mul_f32 v[12:13], v[132:133], v[12:13]
	v_pk_mul_f32 v[14:15], v[134:135], v[14:15]
	v_pk_add_f32 v[18:19], v[116:117], 1.0 op_sel_hi:[1,0]
	v_pk_add_f32 v[16:17], v[118:119], 1.0 op_sel_hi:[1,0]
	v_pk_fma_f32 v[12:13], v[18:19], v[12:13], v[100:101]
	v_pk_fma_f32 v[14:15], v[16:17], v[14:15], v[102:103]
	v_bfe_u32 v154, v12, 16, 1
	v_add3_u32 v12, v12, v154, s2
	v_bfe_u32 v154, v13, 16, 1
	v_lshrrev_b32_e32 v12, 16, v12
	v_add3_u32 v13, v13, v154, s2
	v_and_or_b32 v12, v13, s18, v12
	v_bfe_u32 v13, v14, 16, 1
	v_add3_u32 v13, v14, v13, s2
	v_bfe_u32 v14, v15, 16, 1
	v_lshrrev_b32_e32 v13, 16, v13
	v_add3_u32 v14, v15, v14, s2
	v_and_or_b32 v13, v14, s18, v13
	global_store_dwordx2 v[20:21], v[12:13], off
	s_waitcnt vmcnt(7)
	v_pk_mul_f32 v[8:9], v[136:137], v[8:9]
	v_pk_mul_f32 v[10:11], v[138:139], v[10:11]
	v_pk_add_f32 v[18:19], v[120:121], 1.0 op_sel_hi:[1,0]
	v_pk_add_f32 v[16:17], v[122:123], 1.0 op_sel_hi:[1,0]
	v_pk_fma_f32 v[8:9], v[18:19], v[8:9], v[104:105]
	v_pk_fma_f32 v[10:11], v[16:17], v[10:11], v[106:107]
	v_bfe_u32 v154, v8, 16, 1
	v_add3_u32 v8, v8, v154, s2
	v_bfe_u32 v154, v9, 16, 1
	v_lshrrev_b32_e32 v8, 16, v8
	v_add3_u32 v9, v9, v154, s2
	v_and_or_b32 v8, v9, s18, v8
	v_bfe_u32 v9, v10, 16, 1
	v_add3_u32 v9, v10, v9, s2
	v_bfe_u32 v10, v11, 16, 1
	v_lshrrev_b32_e32 v9, 16, v9
	v_add3_u32 v10, v11, v10, s2
	v_and_or_b32 v9, v10, s18, v9
	global_store_dwordx2 v[20:21], v[8:9], off offset:512
	s_waitcnt vmcnt(5)
	v_pk_mul_f32 v[4:5], v[140:141], v[4:5]
	v_pk_mul_f32 v[6:7], v[142:143], v[6:7]
	v_pk_add_f32 v[18:19], v[124:125], 1.0 op_sel_hi:[1,0]
	v_pk_add_f32 v[16:17], v[126:127], 1.0 op_sel_hi:[1,0]
	v_pk_fma_f32 v[4:5], v[18:19], v[4:5], v[108:109]
	v_pk_fma_f32 v[6:7], v[16:17], v[6:7], v[110:111]
	v_bfe_u32 v154, v4, 16, 1
	v_add3_u32 v4, v4, v154, s2
	v_bfe_u32 v154, v5, 16, 1
	v_lshrrev_b32_e32 v4, 16, v4
	v_add3_u32 v5, v5, v154, s2
	v_and_or_b32 v4, v5, s18, v4
	v_bfe_u32 v5, v6, 16, 1
	v_add3_u32 v5, v6, v5, s2
	v_bfe_u32 v6, v7, 16, 1
	v_lshrrev_b32_e32 v5, 16, v5
	v_add3_u32 v6, v7, v6, s2
	v_and_or_b32 v5, v6, s18, v5
	global_store_dwordx2 v[20:21], v[4:5], off offset:1024
	s_waitcnt vmcnt(3)
	v_pk_mul_f32 v[0:1], v[144:145], v[0:1]
	v_pk_mul_f32 v[2:3], v[146:147], v[2:3]
	v_pk_add_f32 v[18:19], v[128:129], 1.0 op_sel_hi:[1,0]
	v_pk_add_f32 v[16:17], v[130:131], 1.0 op_sel_hi:[1,0]
	v_pk_fma_f32 v[0:1], v[18:19], v[0:1], v[112:113]
	v_pk_fma_f32 v[2:3], v[16:17], v[2:3], v[114:115]
	v_bfe_u32 v154, v0, 16, 1
	v_add3_u32 v0, v0, v154, s2
	v_bfe_u32 v154, v1, 16, 1
	v_lshrrev_b32_e32 v0, 16, v0
	v_add3_u32 v1, v1, v154, s2
	v_and_or_b32 v0, v1, s18, v0
	v_bfe_u32 v1, v2, 16, 1
	v_add3_u32 v1, v2, v1, s2
	v_bfe_u32 v2, v3, 16, 1
	v_lshrrev_b32_e32 v1, 16, v1
	v_add3_u32 v2, v3, v2, s2
	v_and_or_b32 v1, v2, s18, v1
	global_store_dwordx2 v[20:21], v[0:1], off offset:1536
	v_lshl_add_u64 v[20:21], v[20:21], 0, s[22:23]
	s_add_i32 s4, s4, s72
	s_cmpk_lt_i32 s4, 0x4000
	s_cbranch_scc1 .LBB0_831
